# cmp work queue: next item index fetched (global atomic) one item ahead and kept in a spare VGPR, so the per-item atomic round trip is off the critical path
# speedup vs baseline: 1.0034x; 1.0034x over previous
; #define LAS __attribute__((address_space(3)))
; __device__ __forceinline__ bf16x8 scale_frag(bf16x8 q, float c) { float v[8]; unpack8(__builtin_bit_cast(u32x4, q), v); return pack8(v[0] * c, v[1] * c, v[2] * c, v[3] * c, v[4] * c, v[5] * c, v[6] * c, v[7] * c); }
; #define TL_BEGIN(Kg, kpitch, Vg, vpitch, t0, t1) do { TL_FETCH(Kg, kpitch, Vg, vpitch, t0); TL_WRITE(0); __syncthreads(); if ((t0) + 1 < (t1)) TL_FETCH(Kg, kpitch, Vg, vpitch, (t0) + 1); } while (0)
; __device__ __forceinline__ void phase_cmp(const Params& p, LAS unsigned char* lds, const bf16_t* Z, const float* G, const bf16_t* KC, const bf16_t* ACCW, float* ACC, int* IDX, ...
;     LAS int* qsh = (LAS int*)(lds + 106496);
;     LAS bf16_t* Ks0 = (LAS bf16_t*)lds;
;     LAS unsigned* PS = (LAS unsigned*)(lds + 40960);
;     const int r = lane & 31, h = lane >> 5, hh = wid & 3, qs = wid >> 2;
;     const float c = 0.125f * LOG2E;
;     TL_DECL
;     for (;;) {
;         __syncthreads();
;         if (tid == 0) qsh[0] = (int)__hip_atomic_fetch_add(ctr, 1u, __ATOMIC_RELAXED, __HIP_MEMORY_SCOPE_AGENT);
;         __syncthreads();
;         const int qit = qsh[0];
;         if (qit >= 65 + 1024) break;
;         if (qit < 65) {
;             if (qit < 64) { const int gid = qit * 512 + tid, bh = gid >> 12, e = gid & 4095; ml_scan_line(CL + (size_t)bh * 256 * 4096 + e, 4096, GA, MP, bh, e == 0); }
;             else { const int bh = tid >> 6, k = tid & 63; ml_scan_line(NL + (size_t)bh * 256 * 64 + k, 64, GA, MP, bh, false); }
;             continue;
;         }
;         const int bg = (qit - 65) & 3, qb = 255 - ((qit - 65) >> 2), b = bg >> 1, g = bg & 1, head = g * 4 + hh;
;         const bf16_t* Kg = KC + (size_t)(0 * 4 + bg) * 1024 * 64;
;         const bf16_t* Vg = KC + (size_t)(1 * 4 + bg) * 1024 * 64;
;         const int q0w = qb * 64 + 32 * qs, qpos = q0w + r, ql = 32 * qs + r; const size_t row = (size_t)b * SEQ + qpos;
;         bf16x8 qf[4];
; #pragma unroll
;         for (int ks = 0; ks < 4; ++ks) qf[ks] = scale_frag(*(const bf16x8*)(Z + row * ZLD + C_NSQ + head * 64 + 16 * ks + 8 * h), c);
;         float m = NEG, l = 0.f; f32x16 o0, o1;
; #pragma unroll
;         for (int i = 0; i < 16; ++i) { o0[i] = 0.f; o1[i] = 0.f; }
;         const int ncb = 4 * qb + 3, nt = (ncb + 63) >> 6;
;         TL_BEGIN(Kg, 64, Vg, 64, 0, nt);
.LBB0_349:
	s_andn2_b64 vcc, exec, s[2:3]
	s_mov_b32 s2, s12
	v_writelane_b32 v255, s2, 9
	s_nop 1
	v_writelane_b32 v255, s3, 10
	s_cbranch_vccnz .LBB0_523
	s_mov_b64 s[2:3], s[0:1]
	s_load_dwordx2 s[30:31], s[2:3], 0x88
	v_readlane_b32 s2, v254, 0
	s_mov_b32 s3, s86
	s_waitcnt vmcnt(0)
	v_mov_b32_e32 v74, v187
	s_movk_i32 s0, 0x48
	v_readfirstlane_b32 s2, v74
	s_ashr_i32 s29, s2, 6
	s_waitcnt lgkmcnt(0)
	s_add_u32 s86, s30, 0x1e800000
	s_addc_u32 s87, s31, 0
	s_add_u32 s44, s30, 0xd000000
	s_addc_u32 s45, s31, 0
	s_add_u32 s46, s30, 0x16000000
	s_addc_u32 s47, s31, 0
	s_add_u32 s48, s30, 0x1dc00000
	s_addc_u32 s49, s31, 0
	s_lshl_b32 s26, s12, 6
	s_lshl_b64 s[2:3], s[26:27], 2
	s_add_u32 s2, s30, s2
	s_addc_u32 s3, s31, s3
	s_add_u32 s50, s2, 0x1ea22000
	s_addc_u32 s51, s3, 0
	s_lshl_b32 s4, s29, 3
	s_and_b32 s89, s4, 0xffffffe0
	v_mov_b32_e32 v0, s4
	s_movk_i32 s4, 0xffe0
	v_ashrrev_i32_e32 v2, 3, v74
	v_bfi_b32 v7, s4, v0, v74
	v_lshlrev_b32_e32 v0, 3, v74
	v_and_b32_e32 v80, 56, v0
	v_mul_lo_u32 v0, v2, s0
	v_ashrrev_i32_e32 v4, 6, v74
	v_lshlrev_b32_e32 v105, 1, v0
	v_lshlrev_b32_e32 v0, 1, v80
	s_movk_i32 s4, 0x240
	v_and_b32_e32 v77, 63, v74
	v_add3_u32 v117, 0, v105, v0
	v_mul_lo_u32 v0, v4, s4
	v_or_b32_e32 v118, v0, v77
	v_and_b32_e32 v124, 15, v74
	v_or_b32_e32 v0, 32, v77
	v_mul_u32_u24_e32 v125, 0x90, v0
	v_lshlrev_b32_e32 v0, 2, v124
	v_lshl_add_u64 v[90:91], s[48:49], 0, v[0:1]
	v_max_i32_e32 v0, 0x200, v74
	v_sub_u32_e32 v0, v0, v74
	v_ashrrev_i32_e32 v3, 31, v2
	v_add_u32_e32 v0, 0x1ff, v0
	s_and_b32 s88, s29, 3
	v_lshlrev_b64 v[78:79], 7, v[2:3]
	v_ashrrev_i32_e32 v5, 31, v4
	v_lshrrev_b32_e32 v3, 9, v0
	v_bfe_u32 v87, v74, 5, 1
	v_lshlrev_b32_e32 v82, 3, v4
	s_mov_b64 s[4:5], 0x2000
	s_cmp_lt_i32 s29, 64
	v_lshlrev_b64 v[88:89], 16, v[4:5]
	v_lshlrev_b32_e32 v4, 9, v4
	v_add_u32_e32 v3, 1, v3
	v_and_b32_e32 v81, 31, v74
	v_lshlrev_b32_e32 v6, 6, v77
	v_lshl_add_u64 v[84:85], v[78:79], 0, s[4:5]
	v_lshlrev_b32_e32 v120, 4, v87
	s_movk_i32 s4, 0x400
	s_movk_i32 s6, 0x4000
	s_cselect_b64 s[68:69], -1, 0
	v_or_b32_e32 v127, 64, v77
	v_or_b32_e32 v129, 0x80, v77
	v_or_b32_e32 v131, 0xc0, v77
	s_movk_i32 s1, 0x1ff
	v_and_b32_e32 v133, 0xfffffe, v3
	s_add_i32 s16, 0, 0xa000
	v_ashrrev_i32_e32 v5, 31, v4
	v_cmp_eq_u32_e64 s[2:3], 0, v74
	v_lshlrev_b32_e32 v76, 3, v87
	v_ashrrev_i32_e32 v83, 31, v82
	v_lshl_add_u32 v119, v118, 1, 0
	v_lshlrev_b32_e32 v121, 6, v87
	v_mul_u32_u24_e32 v122, 0x90, v81
	v_lshlrev_b32_e32 v86, 2, v87
	v_cmp_gt_i32_e64 s[4:5], s4, v74
	v_cmp_gt_i32_e64 s[6:7], s6, v74
	v_add_u32_e32 v123, 0, v120
	v_cmp_eq_u32_e64 s[8:9], 0, v77
	v_cmp_ne_u32_e64 s[10:11], 0, v77
	v_lshlrev_b32_e32 v126, 8, v77
	v_lshlrev_b32_e32 v128, 8, v127
	v_lshlrev_b32_e32 v130, 8, v129
	v_lshlrev_b32_e32 v132, 8, v131
	v_cmp_lt_u32_e64 s[12:13], s1, v0
	v_lshl_add_u32 v134, v133, 9, v74
	v_add_u32_e32 v75, 0x200, v74
	v_cmp_ne_u32_e64 s[14:15], v3, v133
	v_lshl_add_u32 v135, v7, 2, 0
	v_add_u32_e32 v136, 0x80, v2
	v_lshl_add_u32 v137, v74, 2, s16
	v_add_u32_e32 v138, 0xfffffe00, v74
	v_lshlrev_b64 v[92:93], 2, v[4:5]
	v_lshl_or_b32 v88, v77, 2, v88
	v_lshlrev_b32_e32 v94, 1, v6
	s_and_saveexec_b64 s[16:17], s[2:3]
	v_mov_b32_e32 v0, 1
	global_atomic_add v200, v1, v0, s[50:51] sc0
	s_mov_b64 exec, s[16:17]
	s_branch .LBB0_353

; __device__ __forceinline__ void phase_cmp(const Params& p, LAS unsigned char* lds, const bf16_t* Z, const float* G, const bf16_t* KC, const bf16_t* ACCW, float* ACC, int* IDX, ...
;     ...
;     for (;;) {
;         __syncthreads();
;         if (tid == 0) qsh[0] = (int)__hip_atomic_fetch_add(ctr, 1u, __ATOMIC_RELAXED, __HIP_MEMORY_SCOPE_AGENT);
;         __syncthreads();
;         const int qit = qsh[0];
.LBB0_353:
	s_waitcnt vmcnt(0)
	s_barrier
	s_and_saveexec_b64 s[16:17], s[2:3]
	s_cbranch_execz .LBB0_357
	s_add_i32 s18, 0, 0x1a000
	v_mov_b32_e32 v2, s18
	ds_write_b32 v2, v200
	v_mov_b32_e32 v0, 1
	global_atomic_add v200, v1, v0, s[50:51] sc0

; #define SEAM(k) do { if (coop && (k) + 1 < ph_hi) { for (int rs_ = 0; rs_ < REP_SYNC; ++rs_) { if ((k) == 0) grid.sync(); else xcd_barrier(xbar); } } } while (0)
; __device__ __forceinline__ void xcd_barrier(const XcdBarrier& b) {
;     asm volatile("s_waitcnt vmcnt(0)" ::: "memory");
;     __syncthreads();
;     if (threadIdx.x == 0) {
;         unsigned* bar = b.bar;
;         __builtin_amdgcn_s_waitcnt(0);
;         unsigned nloc = b.st[0], nx = b.st[1];
;         if (nloc == 0u) { xcd_barrier_complete(bar, b.x, nloc, nx); b.st[0] = nloc; b.st[1] = nx; }
; __global__ void __launch_bounds__(512, 2) hybrid_fwd(Params p_unused) {
;     ...
;             SEAM(pb + 2);
.LBB0_477:
	s_waitcnt vmcnt(0)
	v_readlane_b32 s0, v255, 6
	v_readlane_b32 s88, v254, 5
	s_add_i32 s18, s0, 4
	v_readlane_b32 s89, v254, 6
	s_cmp_lt_i32 s18, s89
	v_readlane_b32 s0, v254, 1
	s_cselect_b64 s[2:3], -1, 0
	v_readlane_b32 s1, v254, 2
	s_and_b64 s[2:3], s[0:1], s[2:3]
	s_andn2_b64 vcc, exec, s[2:3]
	v_readlane_b32 s90, v254, 7
	v_readlane_b32 s91, v254, 8
	s_cbranch_vccnz .LBB0_489
	s_waitcnt vmcnt(0)
	v_readlane_b32 s0, v254, 53
	v_readlane_b32 s1, v254, 54
	s_barrier
	s_and_saveexec_b64 s[2:3], s[0:1]
	v_readlane_b32 s0, v254, 3
	v_readlane_b32 s44, v254, 58
	v_readlane_b32 s40, v254, 60
	v_readlane_b32 s46, v254, 62
	v_readlane_b32 s48, v255, 0
	v_readlane_b32 s50, v255, 2
	v_readlane_b32 s1, v254, 4
	v_readlane_b32 s86, v254, 9
	v_readlane_b32 s39, v254, 57
	v_readlane_b32 s45, v254, 59
	v_readlane_b32 s41, v254, 61
	v_readlane_b32 s47, v254, 63
	v_readlane_b32 s49, v255, 1
	v_readlane_b32 s51, v255, 3
	v_readlane_b32 s87, v254, 10
	s_cbranch_execz .LBB0_522
	v_readlane_b32 s4, v254, 51
	s_waitcnt vmcnt(0) expcnt(0) lgkmcnt(0)
	s_nop 0
	v_mov_b32_e32 v0, s4
	ds_read_b32 v3, v0
	v_readlane_b32 s4, v254, 52
	s_waitcnt lgkmcnt(0)
	v_cmp_ne_u32_e32 vcc, 0, v3
	v_mov_b32_e32 v0, s4
	ds_read_b32 v2, v0
	s_cbranch_vccnz .LBB0_493
	s_mov_b32 s10, 1
	s_branch .LBB0_482
